# nt hint on the once-read q/k column loads of GLA pass A (keeps chunk states in the last-level cache)
# baseline (speedup 1.0000x reference)
.LBB0_440:
	s_lshl_b32 s2, s96, 4
	s_lshl_b32 s3, s96, 6
	s_and_b32 s2, s2, 0xfffff000
	s_and_b32 s3, s3, 0xfc0
	s_or_b32 s3, s2, s3
	s_lshl_b32 s2, s96, 2
	v_add_u32_e32 v2, s3, v116
	v_mov_b64_e32 v[4:5], s[4:5]
	s_movk_i32 s24, 0x2200
	s_and_b32 s2, s2, 0x300
	v_mad_i64_i32 v[6:7], s[22:23], v2, s24, v[4:5]
	s_lshl_b32 s74, s2, 1
	v_lshl_add_u64 v[6:7], v[6:7], 0, s[74:75]
	v_lshl_add_u64 v[6:7], v[6:7], 0, v[210:211]
	s_movk_i32 s25, 0x2000
	v_add_co_u32_e64 v8, s[22:23], s25, v6
	s_movk_i32 s26, 0x4000
	s_nop 0
	v_addc_co_u32_e64 v9, s[22:23], 0, v7, s[22:23]
	global_load_ushort v69, v[6:7], off nt
	global_load_ushort v70, v[6:7], off offset:2048 nt
	global_load_ushort v67, v[8:9], off offset:512 nt
	global_load_ushort v68, v[8:9], off offset:2560 nt
	v_add_co_u32_e64 v8, s[22:23], s26, v6
	s_movk_i32 s27, 0x6000
	s_nop 0
	v_addc_co_u32_e64 v9, s[22:23], 0, v7, s[22:23]
	global_load_ushort v65, v[8:9], off offset:1024 nt
	global_load_ushort v66, v[8:9], off offset:3072 nt
	v_add_co_u32_e64 v8, s[22:23], s27, v6
	s_mov_b32 s29, 0x8000
	s_nop 0
	v_addc_co_u32_e64 v9, s[22:23], 0, v7, s[22:23]
	global_load_ushort v63, v[8:9], off offset:1536 nt
	global_load_ushort v64, v[8:9], off offset:3584 nt
	v_add_co_u32_e64 v8, s[22:23], s29, v6
	s_mov_b32 s34, 0xa000
	s_nop 0
	v_addc_co_u32_e64 v9, s[22:23], 0, v7, s[22:23]
	s_mov_b32 s22, 0x9000
	global_load_ushort v61, v[8:9], off offset:2048 nt
	v_add_co_u32_e64 v8, s[22:23], s22, v6
	s_mov_b32 s35, 0xc000
	s_nop 0
	v_addc_co_u32_e64 v9, s[22:23], 0, v7, s[22:23]
	global_load_ushort v62, v[8:9], off nt
	v_add_co_u32_e64 v8, s[22:23], s34, v6
	s_mov_b32 s36, 0xe000
	s_nop 0
	v_addc_co_u32_e64 v9, s[22:23], 0, v7, s[22:23]
	s_mov_b32 s22, 0xb000
	global_load_ushort v59, v[8:9], off offset:2560 nt
	v_add_co_u32_e64 v8, s[22:23], s22, v6
	s_mov_b32 s37, 0xf000
	s_nop 0
	v_addc_co_u32_e64 v9, s[22:23], 0, v7, s[22:23]
	global_load_ushort v60, v[8:9], off offset:512 nt
	v_add_co_u32_e64 v8, s[22:23], s35, v6
	v_add_u32_e32 v3, s3, v95
	s_nop 0
	v_addc_co_u32_e64 v9, s[22:23], 0, v7, s[22:23]
	s_mov_b32 s22, 0xd000
	global_load_ushort v57, v[8:9], off offset:3072 nt
	v_add_co_u32_e64 v8, s[22:23], s22, v6
	v_mov_b32_e32 v109, v211
	s_nop 0
	v_addc_co_u32_e64 v9, s[22:23], 0, v7, s[22:23]
	global_load_ushort v58, v[8:9], off offset:1024 nt
	v_add_co_u32_e64 v8, s[22:23], s36, v6
	v_mov_b32_e32 v85, v211
	s_nop 0
	v_addc_co_u32_e64 v9, s[22:23], 0, v7, s[22:23]
	global_load_ushort v55, v[8:9], off offset:3584 nt
	v_add_co_u32_e64 v8, s[22:23], s37, v6
	s_mov_b32 s3, 0xbfb8aa3b
	s_nop 0
	v_addc_co_u32_e64 v9, s[22:23], 0, v7, s[22:23]
	s_mov_b32 s22, 0x11000
	global_load_ushort v56, v[8:9], off offset:1536 nt
	v_add_co_u32_e64 v8, s[22:23], s22, v6
	s_mov_b32 s38, 0x7f800000
	s_nop 0
	v_addc_co_u32_e64 v9, s[22:23], 0, v7, s[22:23]
	s_mov_b32 s22, 0x13000
	global_load_ushort v53, v[8:9], off nt
	global_load_ushort v54, v[8:9], off offset:2048 nt
	v_add_co_u32_e64 v8, s[22:23], s22, v6
	v_mov_b32_e32 v212, 0x41b17218
	s_nop 0
	v_addc_co_u32_e64 v9, s[22:23], 0, v7, s[22:23]
	s_mov_b32 s22, 0x15000
	global_load_ushort v51, v[8:9], off offset:512 nt
	global_load_ushort v52, v[8:9], off offset:2560 nt
	v_add_co_u32_e64 v8, s[22:23], s22, v6
	s_movk_i32 s28, 0x6000
	s_nop 0
	v_addc_co_u32_e64 v9, s[22:23], 0, v7, s[22:23]
	s_mov_b32 s22, 0x17000
	global_load_ushort v49, v[8:9], off offset:1024 nt
	global_load_ushort v50, v[8:9], off offset:3072 nt
	v_add_co_u32_e64 v8, s[22:23], s22, v6
	s_ashr_i32 s97, s96, 31
	s_nop 0
	v_addc_co_u32_e64 v9, s[22:23], 0, v7, s[22:23]
	s_mov_b32 s22, 0x19000
	global_load_ushort v47, v[8:9], off offset:1536 nt
	global_load_ushort v48, v[8:9], off offset:3584 nt
	v_add_co_u32_e64 v8, s[22:23], s22, v6
	s_nop 1
	v_addc_co_u32_e64 v9, s[22:23], 0, v7, s[22:23]
	s_mov_b32 s22, 0x1a000
	global_load_ushort v45, v[8:9], off offset:2048 nt
	v_add_co_u32_e64 v8, s[22:23], s22, v6
	s_nop 1
	v_addc_co_u32_e64 v9, s[22:23], 0, v7, s[22:23]
	s_mov_b32 s22, 0x1b000
	global_load_ushort v46, v[8:9], off nt
	v_add_co_u32_e64 v8, s[22:23], s22, v6
	s_nop 1
	v_addc_co_u32_e64 v9, s[22:23], 0, v7, s[22:23]
	s_mov_b32 s22, 0x1c000
	global_load_ushort v43, v[8:9], off offset:2560 nt
	v_add_co_u32_e64 v8, s[22:23], s22, v6
	s_nop 1
	v_addc_co_u32_e64 v9, s[22:23], 0, v7, s[22:23]
	s_mov_b32 s22, 0x1d000
	global_load_ushort v44, v[8:9], off offset:512 nt
	v_add_co_u32_e64 v8, s[22:23], s22, v6
	s_nop 1
	v_addc_co_u32_e64 v9, s[22:23], 0, v7, s[22:23]
	s_mov_b32 s22, 0x1e000
	global_load_ushort v41, v[8:9], off offset:3072 nt
	v_add_co_u32_e64 v8, s[22:23], s22, v6
	s_nop 1
	v_addc_co_u32_e64 v9, s[22:23], 0, v7, s[22:23]
	s_mov_b32 s22, 0x1f000
	global_load_ushort v42, v[8:9], off offset:1024 nt
	v_add_co_u32_e64 v8, s[22:23], s22, v6
	s_nop 1
	v_addc_co_u32_e64 v9, s[22:23], 0, v7, s[22:23]
	s_mov_b32 s22, 0x20000
	global_load_ushort v39, v[8:9], off offset:3584 nt
	v_add_co_u32_e64 v8, s[22:23], s22, v6
	s_nop 1
	v_addc_co_u32_e64 v9, s[22:23], 0, v7, s[22:23]
	s_mov_b32 s22, 0x22000
	global_load_ushort v40, v[8:9], off offset:1536 nt
	v_add_co_u32_e64 v8, s[22:23], s22, v6
	s_nop 1
	v_addc_co_u32_e64 v9, s[22:23], 0, v7, s[22:23]
	s_mov_b32 s22, 0x24000
	global_load_ushort v37, v[8:9], off nt
	global_load_ushort v38, v[8:9], off offset:2048 nt
	v_add_co_u32_e64 v8, s[22:23], s22, v6
	s_nop 1
	v_addc_co_u32_e64 v9, s[22:23], 0, v7, s[22:23]
	s_mov_b32 s22, 0x26000
	global_load_ushort v35, v[8:9], off offset:512 nt
	global_load_ushort v36, v[8:9], off offset:2560 nt
	v_add_co_u32_e64 v8, s[22:23], s22, v6
	s_nop 1
	v_addc_co_u32_e64 v9, s[22:23], 0, v7, s[22:23]
	s_mov_b32 s22, 0x28000
	global_load_ushort v33, v[8:9], off offset:1024 nt
	global_load_ushort v34, v[8:9], off offset:3072 nt
	v_add_co_u32_e64 v8, s[22:23], s22, v6
	s_nop 1
	v_addc_co_u32_e64 v9, s[22:23], 0, v7, s[22:23]
	s_mov_b32 s22, 0x2a000
	global_load_ushort v31, v[8:9], off offset:1536 nt
	global_load_ushort v32, v[8:9], off offset:3584 nt
	v_add_co_u32_e64 v8, s[22:23], s22, v6
	s_nop 1
	v_addc_co_u32_e64 v9, s[22:23], 0, v7, s[22:23]
	s_mov_b32 s22, 0x2b000
	global_load_ushort v29, v[8:9], off offset:2048 nt
	v_add_co_u32_e64 v8, s[22:23], s22, v6
	s_nop 1
	v_addc_co_u32_e64 v9, s[22:23], 0, v7, s[22:23]
	s_mov_b32 s22, 0x2c000
	global_load_ushort v30, v[8:9], off nt
	v_add_co_u32_e64 v8, s[22:23], s22, v6
	s_nop 1
	v_addc_co_u32_e64 v9, s[22:23], 0, v7, s[22:23]
	s_mov_b32 s22, 0x2d000
	global_load_ushort v27, v[8:9], off offset:2560 nt
	v_add_co_u32_e64 v8, s[22:23], s22, v6
	s_nop 1
	v_addc_co_u32_e64 v9, s[22:23], 0, v7, s[22:23]
	s_mov_b32 s22, 0x2e000
	global_load_ushort v28, v[8:9], off offset:512 nt
	v_add_co_u32_e64 v8, s[22:23], s22, v6
	s_nop 1
	v_addc_co_u32_e64 v9, s[22:23], 0, v7, s[22:23]
	s_mov_b32 s22, 0x2f000
	global_load_ushort v25, v[8:9], off offset:3072 nt
	v_add_co_u32_e64 v8, s[22:23], s22, v6
	s_nop 1
	v_addc_co_u32_e64 v9, s[22:23], 0, v7, s[22:23]
	s_mov_b32 s22, 0x30000
	global_load_ushort v26, v[8:9], off offset:1024 nt
	v_add_co_u32_e64 v8, s[22:23], s22, v6
	s_nop 1
	v_addc_co_u32_e64 v9, s[22:23], 0, v7, s[22:23]
	s_mov_b32 s22, 0x31000
	global_load_ushort v23, v[8:9], off offset:3584 nt
	v_add_co_u32_e64 v8, s[22:23], s22, v6
	s_nop 1
	v_addc_co_u32_e64 v9, s[22:23], 0, v7, s[22:23]
	s_mov_b32 s22, 0x33000
	global_load_ushort v24, v[8:9], off offset:1536 nt
	v_add_co_u32_e64 v8, s[22:23], s22, v6
	s_nop 1
	v_addc_co_u32_e64 v9, s[22:23], 0, v7, s[22:23]
	s_mov_b32 s22, 0x35000
	global_load_ushort v21, v[8:9], off nt
	global_load_ushort v22, v[8:9], off offset:2048 nt
	v_add_co_u32_e64 v8, s[22:23], s22, v6
	s_nop 1
	v_addc_co_u32_e64 v9, s[22:23], 0, v7, s[22:23]
	s_mov_b32 s22, 0x37000
	global_load_ushort v19, v[8:9], off offset:512 nt
	global_load_ushort v20, v[8:9], off offset:2560 nt
	v_add_co_u32_e64 v8, s[22:23], s22, v6
	s_nop 1
	v_addc_co_u32_e64 v9, s[22:23], 0, v7, s[22:23]
	s_mov_b32 s22, 0x39000
	global_load_ushort v17, v[8:9], off offset:1024 nt
	global_load_ushort v18, v[8:9], off offset:3072 nt
	v_add_co_u32_e64 v8, s[22:23], s22, v6
	s_nop 1
	v_addc_co_u32_e64 v9, s[22:23], 0, v7, s[22:23]
	s_mov_b32 s22, 0x3b000
	global_load_ushort v15, v[8:9], off offset:1536 nt
	global_load_ushort v16, v[8:9], off offset:3584 nt
	v_add_co_u32_e64 v8, s[22:23], s22, v6
	s_nop 1
	v_addc_co_u32_e64 v9, s[22:23], 0, v7, s[22:23]
	s_mov_b32 s22, 0x3c000
	global_load_ushort v13, v[8:9], off offset:2048 nt
	v_add_co_u32_e64 v8, s[22:23], s22, v6
	s_nop 1
	v_addc_co_u32_e64 v9, s[22:23], 0, v7, s[22:23]
	s_mov_b32 s22, 0x3d000
	global_load_ushort v14, v[8:9], off nt
	v_add_co_u32_e64 v8, s[22:23], s22, v6
	s_nop 1
	v_addc_co_u32_e64 v9, s[22:23], 0, v7, s[22:23]
	s_mov_b32 s22, 0x3e000
	global_load_ushort v11, v[8:9], off offset:2560 nt
	v_add_co_u32_e64 v8, s[22:23], s22, v6
	s_nop 1
	v_addc_co_u32_e64 v9, s[22:23], 0, v7, s[22:23]
	s_mov_b32 s22, 0x3f000
	global_load_ushort v12, v[8:9], off offset:512 nt
	v_add_co_u32_e64 v8, s[22:23], s22, v6
	s_nop 1
	v_addc_co_u32_e64 v9, s[22:23], 0, v7, s[22:23]
	s_mov_b32 s22, 0x40000
	s_nop 0
	v_add_co_u32_e64 v72, s[22:23], s22, v6
	global_load_ushort v9, v[8:9], off offset:3072 nt
	s_nop 0
	v_addc_co_u32_e64 v73, s[22:23], 0, v7, s[22:23]
	s_mov_b32 s22, 0x41000
	global_load_ushort v10, v[72:73], off offset:1024 nt
	v_add_co_u32_e64 v72, s[22:23], s22, v6
	s_nop 1
	v_addc_co_u32_e64 v73, s[22:23], 0, v7, s[22:23]
	s_mov_b32 s22, 0x42000
	s_nop 0
	v_add_co_u32_e64 v6, s[22:23], s22, v6
	s_nop 1
	v_addc_co_u32_e64 v7, s[22:23], 0, v7, s[22:23]
	v_mad_i64_i32 v[4:5], s[22:23], v3, s24, v[4:5]
	v_lshl_add_u64 v[4:5], v[4:5], 0, v[108:109]
	v_add_co_u32_e64 v4, s[22:23], s25, v4
	global_load_ushort v6, v[6:7], off offset:1536 nt
	s_nop 0
	v_addc_co_u32_e64 v5, s[22:23], 0, v5, s[22:23]
	global_load_ushort v8, v[72:73], off offset:3584 nt
	s_waitcnt vmcnt(63) expcnt(7) lgkmcnt(15)
	s_barrier
	global_load_dword v3, v[4:5], off
	s_movk_i32 s24, 0x2000
	s_waitcnt vmcnt(0)
	v_lshlrev_b32_e32 v4, 16, v3
	v_and_b32_e32 v5, 0xffff0000, v3
	v_or_b32_e32 v3, s2, v94
	v_lshlrev_b32_e32 v84, 2, v3
	v_lshl_add_u64 v[86:87], s[80:81], 0, v[84:85]
	v_add_co_u32_e64 v72, s[22:23], s25, v86
	ds_write_b64 v117, v[4:5]
	s_nop 0
	v_addc_co_u32_e64 v73, s[22:23], 0, v87, s[22:23]
	global_load_dword v3, v84, s[80:81]
	global_load_dword v5, v[72:73], off offset:-4096
	global_load_dword v4, v[72:73], off
	v_add_co_u32_e64 v72, s[22:23], s26, v86
	v_readlane_b32 s2, v253, 52
	s_nop 0
	v_addc_co_u32_e64 v73, s[22:23], 0, v87, s[22:23]
	v_add_co_u32_e64 v74, s[22:23], s27, v86
	global_load_dword v71, v[72:73], off offset:-4096
	global_load_dword v7, v[72:73], off
	v_addc_co_u32_e64 v75, s[22:23], 0, v87, s[22:23]
	global_load_dword v73, v[74:75], off offset:-4096
	global_load_dword v72, v[74:75], off
	v_add_co_u32_e64 v74, s[22:23], s29, v86
	s_movk_i32 s25, 0x4000
	s_nop 0
	v_addc_co_u32_e64 v75, s[22:23], 0, v87, s[22:23]
	v_add_co_u32_e64 v78, s[22:23], s34, v86
	global_load_dword v76, v[74:75], off offset:-4096
	s_nop 0
	global_load_dword v74, v[74:75], off
	v_addc_co_u32_e64 v79, s[22:23], 0, v87, s[22:23]
	v_add_co_u32_e64 v82, s[22:23], s35, v86
	global_load_dword v80, v[78:79], off offset:-4096
	global_load_dword v77, v[78:79], off
	v_addc_co_u32_e64 v83, s[22:23], 0, v87, s[22:23]
	v_add_co_u32_e64 v88, s[22:23], s36, v86
	global_load_dword v78, v[82:83], off offset:-4096
	global_load_dword v75, v[82:83], off
	v_addc_co_u32_e64 v89, s[22:23], 0, v87, s[22:23]
	v_add_co_u32_e64 v86, s[22:23], s37, v86
	global_load_dword v82, v[88:89], off offset:-4096
	global_load_dword v79, v[88:89], off
	v_addc_co_u32_e64 v87, s[22:23], 0, v87, s[22:23]
	global_load_dword v81, v[86:87], off
	global_load_dword v83, v84, s[88:89]
	v_add_u32_e32 v88, s2, v99
	s_waitcnt lgkmcnt(0)
	s_barrier
	ds_read_b128 v[84:87], v88
	s_mov_b32 s36, 0x800000
	s_mov_b32 s37, 0x3f317217
	s_mov_b32 s2, 0x3d800000
	s_mov_b32 s29, 0xa000
	s_mov_b32 s34, 0xc000
	s_mov_b32 s35, 0xf000
	s_waitcnt vmcnt(15) lgkmcnt(0)
	v_mul_f32_e32 v85, v5, v85
	v_fmac_f32_e32 v85, v3, v84
	s_waitcnt vmcnt(14)
	v_fmac_f32_e32 v85, v4, v86
	s_waitcnt vmcnt(13)
	v_fmac_f32_e32 v85, v71, v87
	s_waitcnt vmcnt(0)
	v_add_f32_e32 v89, v83, v85
	ds_read_b128 v[84:87], v88 offset:16
	s_waitcnt lgkmcnt(0)
	v_mul_f32_e32 v85, v73, v85
	v_fmac_f32_e32 v85, v7, v84
	v_fmac_f32_e32 v85, v72, v86
	v_fmac_f32_e32 v85, v76, v87
	v_add_f32_e32 v89, v89, v85
	ds_read_b128 v[84:87], v88 offset:32
	s_waitcnt lgkmcnt(0)
	v_mul_f32_e32 v85, v80, v85
	v_fmac_f32_e32 v85, v74, v84
	v_fmac_f32_e32 v85, v77, v86
	v_fmac_f32_e32 v85, v78, v87
	v_add_f32_e32 v89, v89, v85
	ds_read_b128 v[84:87], v88 offset:48
	s_waitcnt lgkmcnt(0)
	v_mul_f32_e32 v85, v82, v85
	v_fmac_f32_e32 v85, v75, v84
	v_fmac_f32_e32 v85, v79, v86
	v_fmac_f32_e32 v85, v81, v87
	v_add_f32_e32 v84, v89, v85
	v_min_f32_e32 v85, 0, v84
	v_mul_f32_e64 v84, |v84|, s3
	v_exp_f32_e32 v84, v84
	s_nop 0
	v_add_f32_e32 v84, 1.0, v84
	v_cmp_gt_f32_e64 s[22:23], s36, v84
	s_nop 1
	v_cndmask_b32_e64 v86, 0, 32, s[22:23]
	v_ldexp_f32 v84, v84, v86
	v_log_f32_e32 v84, v84
	s_nop 0
	v_mul_f32_e32 v86, 0x3f317217, v84
	v_fma_f32 v86, v84, s37, -v86
	v_fmac_f32_e32 v86, 0x3377d1cf, v84
	v_fmac_f32_e32 v86, 0x3f317217, v84
	v_cmp_lt_f32_e64 s[26:27], |v84|, s38
	s_nop 1
	v_cndmask_b32_e64 v84, v84, v86, s[26:27]
	v_cndmask_b32_e64 v86, 0, v212, s[22:23]
	v_sub_f32_e32 v84, v84, v86
	ds_read_b128 v[86:89], v155
	v_sub_f32_e32 v84, v85, v84
	v_fma_f32 v84, v84, s2, 0
	s_waitcnt lgkmcnt(0)
	v_mul_f32_e32 v85, v5, v87
	v_fmac_f32_e32 v85, v3, v86
	v_fmac_f32_e32 v85, v4, v88
	v_fmac_f32_e32 v85, v71, v89
	ds_read_b128 v[86:89], v155 offset:16
	v_add_f32_e32 v85, v83, v85
	s_waitcnt lgkmcnt(0)
	v_mul_f32_e32 v87, v73, v87
	v_fmac_f32_e32 v87, v7, v86
	v_fmac_f32_e32 v87, v72, v88
	v_fmac_f32_e32 v87, v76, v89
	v_add_f32_e32 v85, v85, v87
	ds_read_b128 v[86:89], v155 offset:32
	s_waitcnt lgkmcnt(0)
	v_mul_f32_e32 v87, v80, v87
	v_fmac_f32_e32 v87, v74, v86
	v_fmac_f32_e32 v87, v77, v88
	v_fmac_f32_e32 v87, v78, v89
	v_add_f32_e32 v85, v85, v87
	ds_read_b128 v[86:89], v155 offset:48
	s_waitcnt lgkmcnt(0)
	v_mul_f32_e32 v87, v82, v87
	v_fmac_f32_e32 v87, v75, v86
	v_fmac_f32_e32 v87, v79, v88
	v_fmac_f32_e32 v87, v81, v89
	v_add_f32_e32 v85, v85, v87
	v_min_f32_e32 v86, 0, v85
	v_mul_f32_e64 v85, |v85|, s3
	v_exp_f32_e32 v85, v85
	s_nop 0
	v_add_f32_e32 v85, 1.0, v85
	v_cmp_gt_f32_e64 s[22:23], s36, v85
	s_nop 1
	v_cndmask_b32_e64 v87, 0, 32, s[22:23]
	v_ldexp_f32 v85, v85, v87
	v_log_f32_e32 v85, v85
	s_nop 0
	v_mul_f32_e32 v87, 0x3f317217, v85
	v_fma_f32 v87, v85, s37, -v87
	v_fmac_f32_e32 v87, 0x3377d1cf, v85
	v_fmac_f32_e32 v87, 0x3f317217, v85
	v_cmp_lt_f32_e64 s[26:27], |v85|, s38
	s_nop 1
	v_cndmask_b32_e64 v85, v85, v87, s[26:27]
	v_cndmask_b32_e64 v87, 0, v212, s[22:23]
	v_sub_f32_e32 v85, v85, v87
	v_sub_f32_e32 v85, v86, v85
	ds_read_b128 v[86:89], v156
	v_fmamk_f32 v85, v85, 0x3d800000, v84
	s_waitcnt lgkmcnt(0)
	v_mul_f32_e32 v87, v5, v87
	v_fmac_f32_e32 v87, v3, v86
	v_fmac_f32_e32 v87, v4, v88
	v_fmac_f32_e32 v87, v71, v89
	v_add_f32_e32 v90, v83, v87
	ds_read_b128 v[86:89], v156 offset:16
	s_waitcnt lgkmcnt(0)
	v_mul_f32_e32 v87, v73, v87
	v_fmac_f32_e32 v87, v7, v86
	v_fmac_f32_e32 v87, v72, v88
	v_fmac_f32_e32 v87, v76, v89
	v_add_f32_e32 v90, v90, v87
	ds_read_b128 v[86:89], v156 offset:32
	s_waitcnt lgkmcnt(0)
	v_mul_f32_e32 v87, v80, v87
	v_fmac_f32_e32 v87, v74, v86
	v_fmac_f32_e32 v87, v77, v88
	v_fmac_f32_e32 v87, v78, v89
	v_add_f32_e32 v90, v90, v87
	ds_read_b128 v[86:89], v156 offset:48
	s_waitcnt lgkmcnt(0)
	v_mul_f32_e32 v87, v82, v87
	v_fmac_f32_e32 v87, v75, v86
	v_fmac_f32_e32 v87, v79, v88
	v_fmac_f32_e32 v87, v81, v89
	v_add_f32_e32 v86, v90, v87
	v_min_f32_e32 v87, 0, v86
	v_mul_f32_e64 v86, |v86|, s3
	v_exp_f32_e32 v86, v86
	s_nop 0
	v_add_f32_e32 v86, 1.0, v86
	v_cmp_gt_f32_e64 s[22:23], s36, v86
	s_nop 1
	v_cndmask_b32_e64 v88, 0, 32, s[22:23]
	v_ldexp_f32 v86, v86, v88
	v_log_f32_e32 v86, v86
	s_nop 0
	v_mul_f32_e32 v88, 0x3f317217, v86
	v_fma_f32 v88, v86, s37, -v88
	v_fmac_f32_e32 v88, 0x3377d1cf, v86
	v_fmac_f32_e32 v88, 0x3f317217, v86
	v_cmp_lt_f32_e64 s[26:27], |v86|, s38
	s_nop 1
	v_cndmask_b32_e64 v86, v86, v88, s[26:27]
	v_cndmask_b32_e64 v88, 0, v212, s[22:23]
	v_sub_f32_e32 v86, v86, v88
	ds_read_b128 v[88:91], v157
	v_sub_f32_e32 v86, v87, v86
	v_fmamk_f32 v86, v86, 0x3d800000, v85
	s_waitcnt lgkmcnt(0)
	v_mul_f32_e32 v87, v5, v89
	v_fmac_f32_e32 v87, v3, v88
	v_fmac_f32_e32 v87, v4, v90
	v_fmac_f32_e32 v87, v71, v91
	ds_read_b128 v[88:91], v157 offset:16
	v_add_f32_e32 v87, v83, v87
	s_waitcnt lgkmcnt(0)
	v_mul_f32_e32 v89, v73, v89
	v_fmac_f32_e32 v89, v7, v88
	v_fmac_f32_e32 v89, v72, v90
	v_fmac_f32_e32 v89, v76, v91
	v_add_f32_e32 v87, v87, v89
	ds_read_b128 v[88:91], v157 offset:32
	s_waitcnt lgkmcnt(0)
	v_mul_f32_e32 v89, v80, v89
	v_fmac_f32_e32 v89, v74, v88
	v_fmac_f32_e32 v89, v77, v90
	v_fmac_f32_e32 v89, v78, v91
	v_add_f32_e32 v87, v87, v89
	ds_read_b128 v[88:91], v157 offset:48
	s_waitcnt lgkmcnt(0)
	v_mul_f32_e32 v89, v82, v89
	v_fmac_f32_e32 v89, v75, v88
	v_fmac_f32_e32 v89, v79, v90
	v_fmac_f32_e32 v89, v81, v91
	v_add_f32_e32 v87, v87, v89
	v_min_f32_e32 v88, 0, v87
	v_mul_f32_e64 v87, |v87|, s3
	v_exp_f32_e32 v87, v87
	s_nop 0
	v_add_f32_e32 v87, 1.0, v87
	v_cmp_gt_f32_e64 s[22:23], s36, v87
	s_nop 1
	v_cndmask_b32_e64 v89, 0, 32, s[22:23]
	v_ldexp_f32 v87, v87, v89
	v_log_f32_e32 v87, v87
	s_nop 0
	v_mul_f32_e32 v89, 0x3f317217, v87
	v_fma_f32 v89, v87, s37, -v89
	v_fmac_f32_e32 v89, 0x3377d1cf, v87
	v_fmac_f32_e32 v89, 0x3f317217, v87
	v_cmp_lt_f32_e64 s[26:27], |v87|, s38
	s_nop 1
	v_cndmask_b32_e64 v87, v87, v89, s[26:27]
	v_cndmask_b32_e64 v89, 0, v212, s[22:23]
	v_sub_f32_e32 v87, v87, v89
	v_sub_f32_e32 v87, v88, v87
	ds_read_b128 v[88:91], v158
	v_fmamk_f32 v87, v87, 0x3d800000, v86
	s_waitcnt lgkmcnt(0)
	v_mul_f32_e32 v89, v5, v89
	v_fmac_f32_e32 v89, v3, v88
	v_fmac_f32_e32 v89, v4, v90
	v_fmac_f32_e32 v89, v71, v91
	v_add_f32_e32 v92, v83, v89
	ds_read_b128 v[88:91], v158 offset:16
	s_waitcnt lgkmcnt(0)
	v_mul_f32_e32 v89, v73, v89
	v_fmac_f32_e32 v89, v7, v88
	v_fmac_f32_e32 v89, v72, v90
	v_fmac_f32_e32 v89, v76, v91
	v_add_f32_e32 v92, v92, v89
	ds_read_b128 v[88:91], v158 offset:32
	s_waitcnt lgkmcnt(0)
	v_mul_f32_e32 v89, v80, v89
	v_fmac_f32_e32 v89, v74, v88
	v_fmac_f32_e32 v89, v77, v90
	v_fmac_f32_e32 v89, v78, v91
	v_add_f32_e32 v92, v92, v89
	ds_read_b128 v[88:91], v158 offset:48
	s_waitcnt lgkmcnt(0)
	v_mul_f32_e32 v89, v82, v89
	v_fmac_f32_e32 v89, v75, v88
	v_fmac_f32_e32 v89, v79, v90
	v_fmac_f32_e32 v89, v81, v91
	v_add_f32_e32 v88, v92, v89
	v_min_f32_e32 v89, 0, v88
	v_mul_f32_e64 v88, |v88|, s3
	v_exp_f32_e32 v88, v88
	s_nop 0
	v_add_f32_e32 v88, 1.0, v88
	v_cmp_gt_f32_e64 s[22:23], s36, v88
	s_nop 1
	v_cndmask_b32_e64 v90, 0, 32, s[22:23]
	v_ldexp_f32 v88, v88, v90
	v_log_f32_e32 v88, v88
	s_nop 0
	v_mul_f32_e32 v90, 0x3f317217, v88
	v_fma_f32 v90, v88, s37, -v90
	v_fmac_f32_e32 v90, 0x3377d1cf, v88
	v_fmac_f32_e32 v90, 0x3f317217, v88
	v_cmp_lt_f32_e64 s[26:27], |v88|, s38
	s_nop 1
	v_cndmask_b32_e64 v88, v88, v90, s[26:27]
	v_cndmask_b32_e64 v90, 0, v212, s[22:23]
	v_sub_f32_e32 v88, v88, v90
	ds_read_b128 v[90:93], v159
	v_sub_f32_e32 v88, v89, v88
	v_fmamk_f32 v88, v88, 0x3d800000, v87
	s_waitcnt lgkmcnt(0)
	v_mul_f32_e32 v89, v5, v91
	v_fmac_f32_e32 v89, v3, v90
	v_fmac_f32_e32 v89, v4, v92
	v_fmac_f32_e32 v89, v71, v93
	ds_read_b128 v[90:93], v159 offset:16
	v_add_f32_e32 v89, v83, v89
	s_waitcnt lgkmcnt(0)
	v_mul_f32_e32 v91, v73, v91
	v_fmac_f32_e32 v91, v7, v90
	v_fmac_f32_e32 v91, v72, v92
	v_fmac_f32_e32 v91, v76, v93
	v_add_f32_e32 v89, v89, v91
	ds_read_b128 v[90:93], v159 offset:32
	s_waitcnt lgkmcnt(0)
	v_mul_f32_e32 v91, v80, v91
	v_fmac_f32_e32 v91, v74, v90
	v_fmac_f32_e32 v91, v77, v92
	v_fmac_f32_e32 v91, v78, v93
	v_add_f32_e32 v89, v89, v91
	ds_read_b128 v[90:93], v159 offset:48
	s_waitcnt lgkmcnt(0)
	v_mul_f32_e32 v91, v82, v91
	v_fmac_f32_e32 v91, v75, v90
	v_fmac_f32_e32 v91, v79, v92
	v_fmac_f32_e32 v91, v81, v93
	v_add_f32_e32 v89, v89, v91
	v_min_f32_e32 v90, 0, v89
	v_mul_f32_e64 v89, |v89|, s3
	v_exp_f32_e32 v89, v89
	s_nop 0
	v_add_f32_e32 v89, 1.0, v89
	v_cmp_gt_f32_e64 s[22:23], s36, v89
	s_nop 1
	v_cndmask_b32_e64 v91, 0, 32, s[22:23]
	v_ldexp_f32 v89, v89, v91
	v_log_f32_e32 v89, v89
	s_nop 0
	v_mul_f32_e32 v91, 0x3f317217, v89
	v_fma_f32 v91, v89, s37, -v91
	v_fmac_f32_e32 v91, 0x3377d1cf, v89
	v_fmac_f32_e32 v91, 0x3f317217, v89
	v_cmp_lt_f32_e64 s[26:27], |v89|, s38
	s_nop 1
	v_cndmask_b32_e64 v89, v89, v91, s[26:27]
	v_cndmask_b32_e64 v91, 0, v212, s[22:23]
	v_sub_f32_e32 v89, v89, v91
	v_sub_f32_e32 v89, v90, v89
	ds_read_b128 v[90:93], v160
	v_fmamk_f32 v89, v89, 0x3d800000, v88
	s_waitcnt lgkmcnt(0)
	v_mul_f32_e32 v91, v5, v91
	v_fmac_f32_e32 v91, v3, v90
	v_fmac_f32_e32 v91, v4, v92
	v_fmac_f32_e32 v91, v71, v93
	v_add_f32_e32 v109, v83, v91
	ds_read_b128 v[90:93], v160 offset:16
	s_waitcnt lgkmcnt(0)
	v_mul_f32_e32 v91, v73, v91
	v_fmac_f32_e32 v91, v7, v90
	v_fmac_f32_e32 v91, v72, v92
	v_fmac_f32_e32 v91, v76, v93
	v_add_f32_e32 v109, v109, v91
	ds_read_b128 v[90:93], v160 offset:32
	s_waitcnt lgkmcnt(0)
	v_mul_f32_e32 v91, v80, v91
	v_fmac_f32_e32 v91, v74, v90
	v_fmac_f32_e32 v91, v77, v92
	v_fmac_f32_e32 v91, v78, v93
	v_add_f32_e32 v109, v109, v91
	ds_read_b128 v[90:93], v160 offset:48
	ds_read_b128 v[186:189], v161
	ds_read_b128 v[190:193], v161 offset:16
	ds_read_b128 v[194:197], v161 offset:32
	ds_read_b128 v[198:201], v161 offset:48
	s_waitcnt lgkmcnt(4)
	v_mul_f32_e32 v91, v82, v91
	v_fmac_f32_e32 v91, v75, v90
	v_fmac_f32_e32 v91, v79, v92
	v_fmac_f32_e32 v91, v81, v93
	v_add_f32_e32 v90, v109, v91
	v_min_f32_e32 v91, 0, v90
	v_mul_f32_e64 v90, |v90|, s3
	v_exp_f32_e32 v90, v90
	s_nop 0
	v_add_f32_e32 v90, 1.0, v90
	v_cmp_gt_f32_e64 s[22:23], s36, v90
	s_nop 1
	v_cndmask_b32_e64 v92, 0, 32, s[22:23]
	v_ldexp_f32 v90, v90, v92
	v_log_f32_e32 v90, v90
	s_nop 0
	v_mul_f32_e32 v92, 0x3f317217, v90
	v_fma_f32 v92, v90, s37, -v92
	v_fmac_f32_e32 v92, 0x3377d1cf, v90
	v_fmac_f32_e32 v92, 0x3f317217, v90
	v_cmp_lt_f32_e64 s[26:27], |v90|, s38
	s_nop 1
	v_cndmask_b32_e64 v90, v90, v92, s[26:27]
	v_cndmask_b32_e64 v92, 0, v212, s[22:23]
	v_sub_f32_e32 v90, v90, v92
	v_sub_f32_e32 v90, v91, v90
	s_waitcnt lgkmcnt(3)
	v_mul_f32_e32 v91, v5, v187
	v_fmac_f32_e32 v91, v3, v186
	s_waitcnt lgkmcnt(2)
	v_mul_f32_e32 v92, v73, v191
	v_fmac_f32_e32 v91, v4, v188
	v_fmac_f32_e32 v92, v7, v190
	v_fmac_f32_e32 v91, v71, v189
	v_fmac_f32_e32 v92, v72, v192
	v_add_f32_e32 v91, v83, v91
	v_fmac_f32_e32 v92, v76, v193
	v_add_f32_e32 v91, v91, v92
	s_waitcnt lgkmcnt(1)
	v_mul_f32_e32 v92, v80, v195
	v_fmac_f32_e32 v92, v74, v194
	v_fmac_f32_e32 v92, v77, v196
	v_fmac_f32_e32 v92, v78, v197
	v_add_f32_e32 v91, v91, v92
	s_waitcnt lgkmcnt(0)
	v_mul_f32_e32 v92, v82, v199
	v_fmac_f32_e32 v92, v75, v198
	v_fmac_f32_e32 v92, v79, v200
	v_fmac_f32_e32 v92, v81, v201
	v_add_f32_e32 v91, v91, v92
	v_min_f32_e32 v92, 0, v91
	v_mul_f32_e64 v91, |v91|, s3
	v_exp_f32_e32 v91, v91
	ds_read_b128 v[186:189], v162
	ds_read_b128 v[190:193], v162 offset:16
	ds_read_b128 v[194:197], v162 offset:32
	ds_read_b128 v[198:201], v162 offset:48
	v_fmamk_f32 v90, v90, 0x3d800000, v89
	v_add_f32_e32 v91, 1.0, v91
	v_cmp_gt_f32_e64 s[22:23], s36, v91
	s_nop 1
	v_cndmask_b32_e64 v93, 0, 32, s[22:23]
	v_ldexp_f32 v91, v91, v93
	v_log_f32_e32 v91, v91
	s_nop 0
	v_mul_f32_e32 v93, 0x3f317217, v91
	v_fma_f32 v93, v91, s37, -v93
	v_fmac_f32_e32 v93, 0x3377d1cf, v91
	v_fmac_f32_e32 v93, 0x3f317217, v91
	v_cmp_lt_f32_e64 s[26:27], |v91|, s38
	s_nop 1
	v_cndmask_b32_e64 v91, v91, v93, s[26:27]
	v_cndmask_b32_e64 v93, 0, v212, s[22:23]
	v_sub_f32_e32 v91, v91, v93
	v_sub_f32_e32 v91, v92, v91
	s_waitcnt lgkmcnt(3)
	v_mul_f32_e32 v92, v5, v187
	v_fmac_f32_e32 v92, v3, v186
	s_waitcnt lgkmcnt(2)
	v_mul_f32_e32 v93, v73, v191
	v_fmac_f32_e32 v92, v4, v188
	v_fmac_f32_e32 v93, v7, v190
	v_fmac_f32_e32 v92, v71, v189
	v_fmac_f32_e32 v93, v72, v192
	v_add_f32_e32 v92, v83, v92
	v_fmac_f32_e32 v93, v76, v193
	v_add_f32_e32 v92, v92, v93
	s_waitcnt lgkmcnt(1)
	v_mul_f32_e32 v93, v80, v195
	v_fmac_f32_e32 v93, v74, v194
	v_fmac_f32_e32 v93, v77, v196
	v_fmac_f32_e32 v93, v78, v197
	v_add_f32_e32 v92, v92, v93
	s_waitcnt lgkmcnt(0)
	v_mul_f32_e32 v93, v82, v199
	v_fmac_f32_e32 v93, v75, v198
	v_fmac_f32_e32 v93, v79, v200
	v_fmac_f32_e32 v93, v81, v201
	v_add_f32_e32 v92, v92, v93
	v_min_f32_e32 v93, 0, v92
	v_mul_f32_e64 v92, |v92|, s3
	v_exp_f32_e32 v92, v92
	ds_read_b128 v[186:189], v163
	ds_read_b128 v[190:193], v163 offset:16
	ds_read_b128 v[194:197], v163 offset:32
	ds_read_b128 v[198:201], v163 offset:48
	v_fmamk_f32 v91, v91, 0x3d800000, v90
	v_add_f32_e32 v92, 1.0, v92
	v_cmp_gt_f32_e64 s[22:23], s36, v92
	s_nop 1
	v_cndmask_b32_e64 v109, 0, 32, s[22:23]
	v_ldexp_f32 v92, v92, v109
	v_log_f32_e32 v92, v92
	s_nop 0
	v_mul_f32_e32 v109, 0x3f317217, v92
	v_fma_f32 v109, v92, s37, -v109
	v_fmac_f32_e32 v109, 0x3377d1cf, v92
	v_fmac_f32_e32 v109, 0x3f317217, v92
	v_cmp_lt_f32_e64 s[26:27], |v92|, s38
	s_nop 1
	v_cndmask_b32_e64 v92, v92, v109, s[26:27]
	v_cndmask_b32_e64 v109, 0, v212, s[22:23]
	v_sub_f32_e32 v92, v92, v109
	v_sub_f32_e32 v92, v93, v92
	s_waitcnt lgkmcnt(3)
	v_mul_f32_e32 v93, v5, v187
	v_fmac_f32_e32 v93, v3, v186
	s_waitcnt lgkmcnt(2)
	v_mul_f32_e32 v109, v73, v191
	v_fmac_f32_e32 v93, v4, v188
	v_fmac_f32_e32 v109, v7, v190
	v_fmac_f32_e32 v93, v71, v189
	v_fmac_f32_e32 v109, v72, v192
	v_add_f32_e32 v93, v83, v93
	v_fmac_f32_e32 v109, v76, v193
	v_add_f32_e32 v93, v93, v109
	s_waitcnt lgkmcnt(1)
	v_mul_f32_e32 v109, v80, v195
	v_fmac_f32_e32 v109, v74, v194
	v_fmac_f32_e32 v109, v77, v196
	v_fmac_f32_e32 v109, v78, v197
	v_add_f32_e32 v93, v93, v109
	s_waitcnt lgkmcnt(0)
	v_mul_f32_e32 v109, v82, v199
	v_fmac_f32_e32 v109, v75, v198
	v_fmac_f32_e32 v109, v79, v200
	v_fmac_f32_e32 v109, v81, v201
	v_add_f32_e32 v93, v93, v109
	v_min_f32_e32 v109, 0, v93
	v_mul_f32_e64 v93, |v93|, s3
	v_exp_f32_e32 v93, v93
	ds_read_b128 v[186:189], v164
	ds_read_b128 v[190:193], v164 offset:16
	ds_read_b128 v[194:197], v164 offset:32
	ds_read_b128 v[198:201], v164 offset:48
	v_fmamk_f32 v92, v92, 0x3d800000, v91
	v_add_f32_e32 v93, 1.0, v93
	v_cmp_gt_f32_e64 s[22:23], s36, v93
	s_nop 1
	v_cndmask_b32_e64 v111, 0, 32, s[22:23]
	v_ldexp_f32 v93, v93, v111
	v_log_f32_e32 v93, v93
	s_nop 0
	v_mul_f32_e32 v111, 0x3f317217, v93
	v_fma_f32 v111, v93, s37, -v111
	v_fmac_f32_e32 v111, 0x3377d1cf, v93
	v_fmac_f32_e32 v111, 0x3f317217, v93
	v_cmp_lt_f32_e64 s[26:27], |v93|, s38
	s_nop 1
	v_cndmask_b32_e64 v93, v93, v111, s[26:27]
	v_cndmask_b32_e64 v111, 0, v212, s[22:23]
	v_sub_f32_e32 v93, v93, v111
	v_sub_f32_e32 v93, v109, v93
	s_waitcnt lgkmcnt(3)
	v_mul_f32_e32 v109, v5, v187
	v_fmac_f32_e32 v109, v3, v186
	s_waitcnt lgkmcnt(2)
	v_mul_f32_e32 v111, v73, v191
	v_fmac_f32_e32 v109, v4, v188
	v_fmac_f32_e32 v111, v7, v190
	v_fmac_f32_e32 v109, v71, v189
	v_fmac_f32_e32 v111, v72, v192
	v_add_f32_e32 v109, v83, v109
	v_fmac_f32_e32 v111, v76, v193
	v_add_f32_e32 v109, v109, v111
	s_waitcnt lgkmcnt(1)
	v_mul_f32_e32 v111, v80, v195
	v_fmac_f32_e32 v111, v74, v194
	v_fmac_f32_e32 v111, v77, v196
	v_fmac_f32_e32 v111, v78, v197
	v_add_f32_e32 v109, v109, v111
	s_waitcnt lgkmcnt(0)
	v_mul_f32_e32 v111, v82, v199
	v_fmac_f32_e32 v111, v75, v198
	v_fmac_f32_e32 v111, v79, v200
	v_fmac_f32_e32 v111, v81, v201
	v_add_f32_e32 v109, v109, v111
	v_min_f32_e32 v111, 0, v109
	v_mul_f32_e64 v109, |v109|, s3
	v_exp_f32_e32 v109, v109
	ds_read_b128 v[186:189], v165
	ds_read_b128 v[190:193], v165 offset:16
	ds_read_b128 v[194:197], v165 offset:32
	ds_read_b128 v[198:201], v165 offset:48
	v_fmamk_f32 v93, v93, 0x3d800000, v92
	v_add_f32_e32 v109, 1.0, v109
	v_cmp_gt_f32_e64 s[22:23], s36, v109
	s_nop 1
	v_cndmask_b32_e64 v113, 0, 32, s[22:23]
	v_ldexp_f32 v109, v109, v113
	v_log_f32_e32 v109, v109
	s_nop 0
	v_mul_f32_e32 v113, 0x3f317217, v109
	v_fma_f32 v113, v109, s37, -v113
	v_fmac_f32_e32 v113, 0x3377d1cf, v109
	v_fmac_f32_e32 v113, 0x3f317217, v109
	v_cmp_lt_f32_e64 s[26:27], |v109|, s38
	s_nop 1
	v_cndmask_b32_e64 v109, v109, v113, s[26:27]
	v_cndmask_b32_e64 v113, 0, v212, s[22:23]
	v_sub_f32_e32 v109, v109, v113
	v_sub_f32_e32 v109, v111, v109
	s_waitcnt lgkmcnt(3)
	v_mul_f32_e32 v111, v5, v187
	v_fmac_f32_e32 v111, v3, v186
	s_waitcnt lgkmcnt(2)
	v_mul_f32_e32 v113, v73, v191
	v_fmac_f32_e32 v111, v4, v188
	v_fmac_f32_e32 v113, v7, v190
	v_fmac_f32_e32 v111, v71, v189
	v_fmac_f32_e32 v113, v72, v192
	v_add_f32_e32 v111, v83, v111
	v_fmac_f32_e32 v113, v76, v193
	v_add_f32_e32 v111, v111, v113
	s_waitcnt lgkmcnt(1)
	v_mul_f32_e32 v113, v80, v195
	v_fmac_f32_e32 v113, v74, v194
	v_fmac_f32_e32 v113, v77, v196
	v_fmac_f32_e32 v113, v78, v197
	v_add_f32_e32 v111, v111, v113
	s_waitcnt lgkmcnt(0)
	v_mul_f32_e32 v113, v82, v199
	v_fmac_f32_e32 v113, v75, v198
	v_fmac_f32_e32 v113, v79, v200
	v_fmac_f32_e32 v113, v81, v201
	v_add_f32_e32 v111, v111, v113
	v_min_f32_e32 v113, 0, v111
	v_mul_f32_e64 v111, |v111|, s3
	v_exp_f32_e32 v111, v111
	ds_read_b128 v[186:189], v166
	ds_read_b128 v[190:193], v166 offset:16
	ds_read_b128 v[194:197], v166 offset:32
	ds_read_b128 v[198:201], v166 offset:48
	v_fmamk_f32 v109, v109, 0x3d800000, v93
	v_add_f32_e32 v111, 1.0, v111
	v_cmp_gt_f32_e64 s[22:23], s36, v111
	s_nop 1
	v_cndmask_b32_e64 v114, 0, 32, s[22:23]
	v_ldexp_f32 v111, v111, v114
	v_log_f32_e32 v111, v111
	s_nop 0
	v_mul_f32_e32 v114, 0x3f317217, v111
	v_fma_f32 v114, v111, s37, -v114
	v_fmac_f32_e32 v114, 0x3377d1cf, v111
	v_fmac_f32_e32 v114, 0x3f317217, v111
	v_cmp_lt_f32_e64 s[26:27], |v111|, s38
	s_nop 1
	v_cndmask_b32_e64 v111, v111, v114, s[26:27]
	v_cndmask_b32_e64 v114, 0, v212, s[22:23]
	v_sub_f32_e32 v111, v111, v114
	v_sub_f32_e32 v111, v113, v111
	s_waitcnt lgkmcnt(3)
	v_mul_f32_e32 v113, v5, v187
	v_fmac_f32_e32 v113, v3, v186
	s_waitcnt lgkmcnt(2)
	v_mul_f32_e32 v114, v73, v191
	v_fmac_f32_e32 v113, v4, v188
	v_fmac_f32_e32 v114, v7, v190
	v_fmac_f32_e32 v113, v71, v189
	v_fmac_f32_e32 v114, v72, v192
	v_add_f32_e32 v113, v83, v113
	v_fmac_f32_e32 v114, v76, v193
	v_add_f32_e32 v113, v113, v114
	s_waitcnt lgkmcnt(1)
	v_mul_f32_e32 v114, v80, v195
	v_fmac_f32_e32 v114, v74, v194
	v_fmac_f32_e32 v114, v77, v196
	v_fmac_f32_e32 v114, v78, v197
	v_add_f32_e32 v113, v113, v114
	s_waitcnt lgkmcnt(0)
	v_mul_f32_e32 v114, v82, v199
	v_fmac_f32_e32 v114, v75, v198
	v_fmac_f32_e32 v114, v79, v200
	v_fmac_f32_e32 v114, v81, v201
	v_add_f32_e32 v113, v113, v114
	v_min_f32_e32 v114, 0, v113
	v_mul_f32_e64 v113, |v113|, s3
	v_exp_f32_e32 v113, v113
	ds_read_b128 v[186:189], v167
	ds_read_b128 v[190:193], v167 offset:16
	ds_read_b128 v[194:197], v167 offset:32
	ds_read_b128 v[198:201], v167 offset:48
	v_fmamk_f32 v111, v111, 0x3d800000, v109
	v_add_f32_e32 v113, 1.0, v113
	v_cmp_gt_f32_e64 s[22:23], s36, v113
	s_nop 1
	v_cndmask_b32_e64 v115, 0, 32, s[22:23]
	v_ldexp_f32 v113, v113, v115
	v_log_f32_e32 v113, v113
	s_nop 0
	v_mul_f32_e32 v115, 0x3f317217, v113
	v_fma_f32 v115, v113, s37, -v115
	v_fmac_f32_e32 v115, 0x3377d1cf, v113
	v_fmac_f32_e32 v115, 0x3f317217, v113
	v_cmp_lt_f32_e64 s[26:27], |v113|, s38
	s_nop 1
	v_cndmask_b32_e64 v113, v113, v115, s[26:27]
	v_cndmask_b32_e64 v115, 0, v212, s[22:23]
	v_sub_f32_e32 v113, v113, v115
	v_sub_f32_e32 v113, v114, v113
	s_waitcnt lgkmcnt(3)
	v_mul_f32_e32 v114, v5, v187
	v_fmac_f32_e32 v114, v3, v186
	s_waitcnt lgkmcnt(2)
	v_mul_f32_e32 v115, v73, v191
	v_fmac_f32_e32 v114, v4, v188
	v_fmac_f32_e32 v115, v7, v190
	v_fmac_f32_e32 v114, v71, v189
	v_fmac_f32_e32 v115, v72, v192
	v_add_f32_e32 v114, v83, v114
	v_fmac_f32_e32 v115, v76, v193
	v_add_f32_e32 v114, v114, v115
	s_waitcnt lgkmcnt(1)
	v_mul_f32_e32 v115, v80, v195
	v_fmac_f32_e32 v115, v74, v194
	v_fmac_f32_e32 v115, v77, v196
	v_fmac_f32_e32 v115, v78, v197
	v_add_f32_e32 v114, v114, v115
	s_waitcnt lgkmcnt(0)
	v_mul_f32_e32 v115, v82, v199
	v_fmac_f32_e32 v115, v75, v198
	v_fmac_f32_e32 v115, v79, v200
	v_fmac_f32_e32 v115, v81, v201
	v_add_f32_e32 v114, v114, v115
	v_min_f32_e32 v115, 0, v114
	v_mul_f32_e64 v114, |v114|, s3
	v_exp_f32_e32 v114, v114
	v_fmamk_f32 v113, v113, 0x3d800000, v111
	v_add_f32_e32 v114, 1.0, v114
	v_cmp_gt_f32_e64 s[22:23], s36, v114
	s_nop 1
	v_cndmask_b32_e64 v186, 0, 32, s[22:23]
	v_ldexp_f32 v114, v114, v186
	v_log_f32_e32 v114, v114
	s_nop 0
	v_mul_f32_e32 v186, 0x3f317217, v114
	v_fma_f32 v186, v114, s37, -v186
	v_fmac_f32_e32 v186, 0x3377d1cf, v114
	v_fmac_f32_e32 v186, 0x3f317217, v114
	v_cmp_lt_f32_e64 s[26:27], |v114|, s38
	s_nop 1
	v_cndmask_b32_e64 v114, v114, v186, s[26:27]
	v_cndmask_b32_e64 v186, 0, v212, s[22:23]
	v_sub_f32_e32 v114, v114, v186
	ds_read_b128 v[186:189], v168
	ds_read_b128 v[190:193], v168 offset:16
	ds_read_b128 v[194:197], v168 offset:32
	ds_read_b128 v[198:201], v168 offset:48
	v_sub_f32_e32 v114, v115, v114
	s_waitcnt lgkmcnt(3)
	v_mul_f32_e32 v115, v5, v187
	v_fmac_f32_e32 v115, v3, v186
	s_waitcnt lgkmcnt(2)
	v_mul_f32_e32 v186, v73, v191
	v_fmac_f32_e32 v115, v4, v188
	v_fmac_f32_e32 v186, v7, v190
	v_fmac_f32_e32 v115, v71, v189
	v_fmac_f32_e32 v186, v72, v192
	v_add_f32_e32 v115, v83, v115
	v_fmac_f32_e32 v186, v76, v193
	v_add_f32_e32 v115, v115, v186
	s_waitcnt lgkmcnt(1)
	v_mul_f32_e32 v186, v80, v195
	v_fmac_f32_e32 v186, v74, v194
	v_fmac_f32_e32 v186, v77, v196
	v_fmac_f32_e32 v186, v78, v197
	v_add_f32_e32 v115, v115, v186
	s_waitcnt lgkmcnt(0)
	v_mul_f32_e32 v186, v82, v199
	v_fmac_f32_e32 v186, v75, v198
	v_fmac_f32_e32 v186, v79, v200
	v_fmac_f32_e32 v186, v81, v201
	v_add_f32_e32 v115, v115, v186
	v_min_f32_e32 v186, 0, v115
	v_mul_f32_e64 v115, |v115|, s3
	v_exp_f32_e32 v115, v115
	v_fmamk_f32 v114, v114, 0x3d800000, v113
	v_add_f32_e32 v115, 1.0, v115
	v_cmp_gt_f32_e64 s[22:23], s36, v115
	s_nop 1
	v_cndmask_b32_e64 v187, 0, 32, s[22:23]
	v_ldexp_f32 v115, v115, v187
	v_log_f32_e32 v115, v115
	s_nop 0
	v_mul_f32_e32 v187, 0x3f317217, v115
	v_fma_f32 v187, v115, s37, -v187
	v_fmac_f32_e32 v187, 0x3377d1cf, v115
	v_fmac_f32_e32 v187, 0x3f317217, v115
	v_cmp_lt_f32_e64 s[26:27], |v115|, s38
	s_nop 1
	v_cndmask_b32_e64 v115, v115, v187, s[26:27]
	v_cndmask_b32_e64 v187, 0, v212, s[22:23]
	v_sub_f32_e32 v115, v115, v187
	v_sub_f32_e32 v115, v186, v115
	ds_read_b128 v[186:189], v169
	ds_read_b128 v[190:193], v169 offset:16
	ds_read_b128 v[194:197], v169 offset:32
	ds_read_b128 v[198:201], v169 offset:48
	v_fmamk_f32 v115, v115, 0x3d800000, v114
	s_waitcnt lgkmcnt(3)
	v_mul_f32_e32 v187, v5, v187
	v_fmac_f32_e32 v187, v3, v186
	v_fmac_f32_e32 v187, v4, v188
	v_fmac_f32_e32 v187, v71, v189
	v_add_f32_e32 v186, v83, v187
	s_waitcnt lgkmcnt(2)
	v_mul_f32_e32 v187, v73, v191
	v_fmac_f32_e32 v187, v7, v190
	v_fmac_f32_e32 v187, v72, v192
	v_fmac_f32_e32 v187, v76, v193
	v_add_f32_e32 v186, v186, v187
	s_waitcnt lgkmcnt(1)
	v_mul_f32_e32 v187, v80, v195
	v_fmac_f32_e32 v187, v74, v194
	v_fmac_f32_e32 v187, v77, v196
	v_fmac_f32_e32 v187, v78, v197
	v_add_f32_e32 v186, v186, v187
	s_waitcnt lgkmcnt(0)
	v_mul_f32_e32 v187, v82, v199
	v_fmac_f32_e32 v187, v75, v198
	v_fmac_f32_e32 v187, v79, v200
	v_fmac_f32_e32 v187, v81, v201
	v_add_f32_e32 v186, v186, v187
	v_min_f32_e32 v187, 0, v186
	v_mul_f32_e64 v186, |v186|, s3
	v_exp_f32_e32 v186, v186
	s_nop 0
	v_add_f32_e32 v186, 1.0, v186
	v_cmp_gt_f32_e64 s[22:23], s36, v186
	s_nop 1
	v_cndmask_b32_e64 v188, 0, 32, s[22:23]
	v_ldexp_f32 v186, v186, v188
	v_log_f32_e32 v186, v186
	s_nop 0
	v_mul_f32_e32 v188, 0x3f317217, v186
	v_fma_f32 v188, v186, s37, -v188
	v_fmac_f32_e32 v188, 0x3377d1cf, v186
	v_fmac_f32_e32 v188, 0x3f317217, v186
	v_cmp_lt_f32_e64 s[26:27], |v186|, s38
	s_nop 1
	v_cndmask_b32_e64 v186, v186, v188, s[26:27]
	v_cndmask_b32_e64 v188, 0, v212, s[22:23]
	v_sub_f32_e32 v186, v186, v188
	ds_read_b128 v[188:191], v170
	ds_read_b128 v[192:195], v170 offset:16
	ds_read_b128 v[196:199], v170 offset:32
	ds_read_b128 v[200:203], v170 offset:48
	v_sub_f32_e32 v186, v187, v186
	s_waitcnt lgkmcnt(3)
	v_mul_f32_e32 v187, v5, v189
	v_fmac_f32_e32 v187, v3, v188
	s_waitcnt lgkmcnt(2)
	v_mul_f32_e32 v188, v73, v193
	v_fmac_f32_e32 v187, v4, v190
	v_fmac_f32_e32 v188, v7, v192
	v_fmac_f32_e32 v187, v71, v191
	v_fmac_f32_e32 v188, v72, v194
	v_add_f32_e32 v187, v83, v187
	v_fmac_f32_e32 v188, v76, v195
	v_add_f32_e32 v187, v187, v188
	s_waitcnt lgkmcnt(1)
	v_mul_f32_e32 v188, v80, v197
	v_fmac_f32_e32 v188, v74, v196
	v_fmac_f32_e32 v188, v77, v198
	v_fmac_f32_e32 v188, v78, v199
	v_add_f32_e32 v187, v187, v188
	s_waitcnt lgkmcnt(0)
	v_mul_f32_e32 v188, v82, v201
	v_fmac_f32_e32 v188, v75, v200
	v_fmac_f32_e32 v188, v79, v202
	v_fmac_f32_e32 v188, v81, v203
	v_add_f32_e32 v187, v187, v188
	v_min_f32_e32 v188, 0, v187
	v_mul_f32_e64 v187, |v187|, s3
	v_exp_f32_e32 v187, v187
	v_fmamk_f32 v186, v186, 0x3d800000, v115
	v_add_f32_e32 v187, 1.0, v187
	v_cmp_gt_f32_e64 s[22:23], s36, v187
	s_nop 1
	v_cndmask_b32_e64 v189, 0, 32, s[22:23]
	v_ldexp_f32 v187, v187, v189
	v_log_f32_e32 v187, v187
	s_nop 0
	v_mul_f32_e32 v189, 0x3f317217, v187
	v_fma_f32 v189, v187, s37, -v189
	v_fmac_f32_e32 v189, 0x3377d1cf, v187
	v_fmac_f32_e32 v189, 0x3f317217, v187
	v_cmp_lt_f32_e64 s[26:27], |v187|, s38
	s_nop 1
	v_cndmask_b32_e64 v187, v187, v189, s[26:27]
	v_cndmask_b32_e64 v189, 0, v212, s[22:23]
	v_sub_f32_e32 v187, v187, v189
	v_sub_f32_e32 v187, v188, v187
	ds_read_b128 v[188:191], v171
	ds_read_b128 v[192:195], v171 offset:16
	ds_read_b128 v[196:199], v171 offset:32
	ds_read_b128 v[200:203], v171 offset:48
	v_fmamk_f32 v187, v187, 0x3d800000, v186
	s_waitcnt lgkmcnt(3)
	v_mul_f32_e32 v189, v5, v189
	v_fmac_f32_e32 v189, v3, v188
	v_fmac_f32_e32 v189, v4, v190
	v_fmac_f32_e32 v189, v71, v191
	v_add_f32_e32 v188, v83, v189
	s_waitcnt lgkmcnt(2)
	v_mul_f32_e32 v189, v73, v193
	v_fmac_f32_e32 v189, v7, v192
	v_fmac_f32_e32 v189, v72, v194
	v_fmac_f32_e32 v189, v76, v195
	v_add_f32_e32 v188, v188, v189
	s_waitcnt lgkmcnt(1)
	v_mul_f32_e32 v189, v80, v197
	v_fmac_f32_e32 v189, v74, v196
	v_fmac_f32_e32 v189, v77, v198
	v_fmac_f32_e32 v189, v78, v199
	v_add_f32_e32 v188, v188, v189
	s_waitcnt lgkmcnt(0)
	v_mul_f32_e32 v189, v82, v201
	v_fmac_f32_e32 v189, v75, v200
	v_fmac_f32_e32 v189, v79, v202
	v_fmac_f32_e32 v189, v81, v203
	v_add_f32_e32 v188, v188, v189
	v_min_f32_e32 v189, 0, v188
	v_mul_f32_e64 v188, |v188|, s3
	v_exp_f32_e32 v188, v188
	s_nop 0
	v_add_f32_e32 v188, 1.0, v188
	v_cmp_gt_f32_e64 s[22:23], s36, v188
	s_nop 1
	v_cndmask_b32_e64 v190, 0, 32, s[22:23]
	v_ldexp_f32 v188, v188, v190
	v_log_f32_e32 v188, v188
	s_nop 0
	v_mul_f32_e32 v190, 0x3f317217, v188
	v_fma_f32 v190, v188, s37, -v190
	v_fmac_f32_e32 v190, 0x3377d1cf, v188
	v_fmac_f32_e32 v190, 0x3f317217, v188
	v_cmp_lt_f32_e64 s[26:27], |v188|, s38
	s_nop 1
	v_cndmask_b32_e64 v188, v188, v190, s[26:27]
	v_cndmask_b32_e64 v190, 0, v212, s[22:23]
	v_sub_f32_e32 v188, v188, v190
	ds_read_b128 v[190:193], v172
	ds_read_b128 v[194:197], v172 offset:16
	ds_read_b128 v[198:201], v172 offset:32
	ds_read_b128 v[202:205], v172 offset:48
	v_sub_f32_e32 v188, v189, v188
	s_waitcnt lgkmcnt(3)
	v_mul_f32_e32 v189, v5, v191
	v_fmac_f32_e32 v189, v3, v190
	s_waitcnt lgkmcnt(2)
	v_mul_f32_e32 v190, v73, v195
	v_fmac_f32_e32 v189, v4, v192
	v_fmac_f32_e32 v190, v7, v194
	v_fmac_f32_e32 v189, v71, v193
	v_fmac_f32_e32 v190, v72, v196
	v_add_f32_e32 v189, v83, v189
	v_fmac_f32_e32 v190, v76, v197
	v_add_f32_e32 v189, v189, v190
	s_waitcnt lgkmcnt(1)
	v_mul_f32_e32 v190, v80, v199
	v_fmac_f32_e32 v190, v74, v198
	v_fmac_f32_e32 v190, v77, v200
	v_fmac_f32_e32 v190, v78, v201
	v_add_f32_e32 v189, v189, v190
	s_waitcnt lgkmcnt(0)
	v_mul_f32_e32 v190, v82, v203
	v_fmac_f32_e32 v190, v75, v202
	v_fmac_f32_e32 v190, v79, v204
	v_fmac_f32_e32 v190, v81, v205
	v_add_f32_e32 v189, v189, v190
	v_min_f32_e32 v190, 0, v189
	v_mul_f32_e64 v189, |v189|, s3
	v_exp_f32_e32 v189, v189
	v_fmamk_f32 v188, v188, 0x3d800000, v187
	v_add_f32_e32 v189, 1.0, v189
	v_cmp_gt_f32_e64 s[22:23], s36, v189
	s_nop 1
	v_cndmask_b32_e64 v191, 0, 32, s[22:23]
	v_ldexp_f32 v189, v189, v191
	v_log_f32_e32 v189, v189
	s_nop 0
	v_mul_f32_e32 v191, 0x3f317217, v189
	v_fma_f32 v191, v189, s37, -v191
	v_fmac_f32_e32 v191, 0x3377d1cf, v189
	v_fmac_f32_e32 v191, 0x3f317217, v189
	v_cmp_lt_f32_e64 s[26:27], |v189|, s38
	s_nop 1
	v_cndmask_b32_e64 v189, v189, v191, s[26:27]
	v_cndmask_b32_e64 v191, 0, v212, s[22:23]
	v_sub_f32_e32 v189, v189, v191
	v_sub_f32_e32 v189, v190, v189
	ds_read_b128 v[190:193], v173
	ds_read_b128 v[194:197], v173 offset:16
	ds_read_b128 v[198:201], v173 offset:32
	ds_read_b128 v[202:205], v173 offset:48
	v_fmamk_f32 v189, v189, 0x3d800000, v188
	s_waitcnt lgkmcnt(3)
	v_mul_f32_e32 v191, v5, v191
	v_fmac_f32_e32 v191, v3, v190
	v_fmac_f32_e32 v191, v4, v192
	v_fmac_f32_e32 v191, v71, v193
	v_add_f32_e32 v190, v83, v191
	s_waitcnt lgkmcnt(2)
	v_mul_f32_e32 v191, v73, v195
	v_fmac_f32_e32 v191, v7, v194
	v_fmac_f32_e32 v191, v72, v196
	v_fmac_f32_e32 v191, v76, v197
	v_add_f32_e32 v190, v190, v191
	s_waitcnt lgkmcnt(1)
	v_mul_f32_e32 v191, v80, v199
	v_fmac_f32_e32 v191, v74, v198
	v_fmac_f32_e32 v191, v77, v200
	v_fmac_f32_e32 v191, v78, v201
	v_add_f32_e32 v190, v190, v191
	s_waitcnt lgkmcnt(0)
	v_mul_f32_e32 v191, v82, v203
	v_fmac_f32_e32 v191, v75, v202
	v_fmac_f32_e32 v191, v79, v204
	v_fmac_f32_e32 v191, v81, v205
	v_add_f32_e32 v190, v190, v191
	v_min_f32_e32 v191, 0, v190
	v_mul_f32_e64 v190, |v190|, s3
	v_exp_f32_e32 v190, v190
	s_nop 0
	v_add_f32_e32 v190, 1.0, v190
	v_cmp_gt_f32_e64 s[22:23], s36, v190
	s_nop 1
	v_cndmask_b32_e64 v192, 0, 32, s[22:23]
	v_ldexp_f32 v190, v190, v192
	v_log_f32_e32 v190, v190
	s_nop 0
	v_mul_f32_e32 v192, 0x3f317217, v190
	v_fma_f32 v192, v190, s37, -v192
	v_fmac_f32_e32 v192, 0x3377d1cf, v190
	v_fmac_f32_e32 v192, 0x3f317217, v190
	v_cmp_lt_f32_e64 s[26:27], |v190|, s38
	s_nop 1
	v_cndmask_b32_e64 v190, v190, v192, s[26:27]
	v_cndmask_b32_e64 v192, 0, v212, s[22:23]
	v_sub_f32_e32 v190, v190, v192
	ds_read_b128 v[192:195], v174
	ds_read_b128 v[196:199], v174 offset:16
	ds_read_b128 v[200:203], v174 offset:32
	ds_read_b128 v[204:207], v174 offset:48
	v_sub_f32_e32 v190, v191, v190
	s_waitcnt lgkmcnt(3)
	v_mul_f32_e32 v191, v5, v193
	v_fmac_f32_e32 v191, v3, v192
	s_waitcnt lgkmcnt(2)
	v_mul_f32_e32 v192, v73, v197
	v_fmac_f32_e32 v191, v4, v194
	v_fmac_f32_e32 v192, v7, v196
	v_fmac_f32_e32 v191, v71, v195
	v_fmac_f32_e32 v192, v72, v198
	v_add_f32_e32 v191, v83, v191
	v_fmac_f32_e32 v192, v76, v199
	v_add_f32_e32 v191, v191, v192
	s_waitcnt lgkmcnt(1)
	v_mul_f32_e32 v192, v80, v201
	v_fmac_f32_e32 v192, v74, v200
	v_fmac_f32_e32 v192, v77, v202
	v_fmac_f32_e32 v192, v78, v203
	v_add_f32_e32 v191, v191, v192
	s_waitcnt lgkmcnt(0)
	v_mul_f32_e32 v192, v82, v205
	v_fmac_f32_e32 v192, v75, v204
	v_fmac_f32_e32 v192, v79, v206
	v_fmac_f32_e32 v192, v81, v207
	v_add_f32_e32 v191, v191, v192
	v_min_f32_e32 v192, 0, v191
	v_mul_f32_e64 v191, |v191|, s3
	v_exp_f32_e32 v191, v191
	v_fmamk_f32 v190, v190, 0x3d800000, v189
	v_add_f32_e32 v191, 1.0, v191
	v_cmp_gt_f32_e64 s[22:23], s36, v191
	s_nop 1
	v_cndmask_b32_e64 v193, 0, 32, s[22:23]
	v_ldexp_f32 v191, v191, v193
	v_log_f32_e32 v191, v191
	s_nop 0
	v_mul_f32_e32 v193, 0x3f317217, v191
	v_fma_f32 v193, v191, s37, -v193
	v_fmac_f32_e32 v193, 0x3377d1cf, v191
	v_fmac_f32_e32 v193, 0x3f317217, v191
	v_cmp_lt_f32_e64 s[26:27], |v191|, s38
	s_nop 1
	v_cndmask_b32_e64 v191, v191, v193, s[26:27]
	v_cndmask_b32_e64 v193, 0, v212, s[22:23]
	v_sub_f32_e32 v191, v191, v193
	v_sub_f32_e32 v191, v192, v191
	ds_read_b128 v[192:195], v175
	ds_read_b128 v[196:199], v175 offset:16
	ds_read_b128 v[200:203], v175 offset:32
	ds_read_b128 v[204:207], v175 offset:48
	v_fmamk_f32 v191, v191, 0x3d800000, v190
	s_waitcnt lgkmcnt(3)
	v_mul_f32_e32 v193, v5, v193
	v_fmac_f32_e32 v193, v3, v192
	v_fmac_f32_e32 v193, v4, v194
	v_fmac_f32_e32 v193, v71, v195
	v_add_f32_e32 v192, v83, v193
	s_waitcnt lgkmcnt(2)
	v_mul_f32_e32 v193, v73, v197
	v_fmac_f32_e32 v193, v7, v196
	v_fmac_f32_e32 v193, v72, v198
	v_fmac_f32_e32 v193, v76, v199
	v_add_f32_e32 v192, v192, v193
	s_waitcnt lgkmcnt(1)
	v_mul_f32_e32 v193, v80, v201
	v_fmac_f32_e32 v193, v74, v200
	v_fmac_f32_e32 v193, v77, v202
	v_fmac_f32_e32 v193, v78, v203
	v_add_f32_e32 v192, v192, v193
	s_waitcnt lgkmcnt(0)
	v_mul_f32_e32 v193, v82, v205
	v_fmac_f32_e32 v193, v75, v204
	v_fmac_f32_e32 v193, v79, v206
	v_fmac_f32_e32 v193, v81, v207
	v_add_f32_e32 v192, v192, v193
	v_min_f32_e32 v193, 0, v192
	v_mul_f32_e64 v192, |v192|, s3
	v_exp_f32_e32 v192, v192
	s_nop 0
	v_add_f32_e32 v192, 1.0, v192
	v_cmp_gt_f32_e64 s[22:23], s36, v192
	s_nop 1
	v_cndmask_b32_e64 v194, 0, 32, s[22:23]
	v_ldexp_f32 v192, v192, v194
	v_log_f32_e32 v192, v192
	s_nop 0
	v_mul_f32_e32 v194, 0x3f317217, v192
	v_fma_f32 v194, v192, s37, -v194
	v_fmac_f32_e32 v194, 0x3377d1cf, v192
	v_fmac_f32_e32 v194, 0x3f317217, v192
	v_cmp_lt_f32_e64 s[26:27], |v192|, s38
	s_nop 1
	v_cndmask_b32_e64 v192, v192, v194, s[26:27]
	v_cndmask_b32_e64 v194, 0, v212, s[22:23]
	v_sub_f32_e32 v192, v192, v194
	ds_read_b128 v[194:197], v176
	ds_read_b128 v[198:201], v176 offset:16
	ds_read_b128 v[202:205], v176 offset:32
	ds_read_b128 v[206:209], v176 offset:48
	v_sub_f32_e32 v192, v193, v192
	s_waitcnt lgkmcnt(3)
	v_mul_f32_e32 v193, v5, v195
	v_fmac_f32_e32 v193, v3, v194
	s_waitcnt lgkmcnt(2)
	v_mul_f32_e32 v194, v73, v199
	v_fmac_f32_e32 v193, v4, v196
	v_fmac_f32_e32 v194, v7, v198
	v_fmac_f32_e32 v193, v71, v197
	v_fmac_f32_e32 v194, v72, v200
	v_add_f32_e32 v193, v83, v193
	v_fmac_f32_e32 v194, v76, v201
	v_add_f32_e32 v193, v193, v194
	s_waitcnt lgkmcnt(1)
	v_mul_f32_e32 v194, v80, v203
	v_fmac_f32_e32 v194, v74, v202
	v_fmac_f32_e32 v194, v77, v204
	v_fmac_f32_e32 v194, v78, v205
	v_add_f32_e32 v193, v193, v194
	s_waitcnt lgkmcnt(0)
	v_mul_f32_e32 v194, v82, v207
	v_fmac_f32_e32 v194, v75, v206
	v_fmac_f32_e32 v194, v79, v208
	v_fmac_f32_e32 v194, v81, v209
	v_add_f32_e32 v193, v193, v194
	v_min_f32_e32 v194, 0, v193
	v_mul_f32_e64 v193, |v193|, s3
	v_exp_f32_e32 v193, v193
	v_fmamk_f32 v192, v192, 0x3d800000, v191
	v_add_f32_e32 v193, 1.0, v193
	v_cmp_gt_f32_e64 s[22:23], s36, v193
	s_nop 1
	v_cndmask_b32_e64 v195, 0, 32, s[22:23]
	v_ldexp_f32 v193, v193, v195
	v_log_f32_e32 v193, v193
	s_nop 0
	v_mul_f32_e32 v195, 0x3f317217, v193
	v_fma_f32 v195, v193, s37, -v195
	v_fmac_f32_e32 v195, 0x3377d1cf, v193
	v_fmac_f32_e32 v195, 0x3f317217, v193
	v_cmp_lt_f32_e64 s[26:27], |v193|, s38
	s_nop 1
	v_cndmask_b32_e64 v193, v193, v195, s[26:27]
	v_cndmask_b32_e64 v195, 0, v212, s[22:23]
	v_sub_f32_e32 v193, v193, v195
	v_sub_f32_e32 v193, v194, v193
	ds_read_b128 v[194:197], v177
	ds_read_b128 v[198:201], v177 offset:16
	ds_read_b128 v[202:205], v177 offset:32
	ds_read_b128 v[206:209], v177 offset:48
	v_fmamk_f32 v193, v193, 0x3d800000, v192
	s_waitcnt lgkmcnt(3)
	v_mul_f32_e32 v195, v5, v195
	v_fmac_f32_e32 v195, v3, v194
	v_fmac_f32_e32 v195, v4, v196
	v_fmac_f32_e32 v195, v71, v197
	v_add_f32_e32 v194, v83, v195
	s_waitcnt lgkmcnt(2)
	v_mul_f32_e32 v195, v73, v199
	v_fmac_f32_e32 v195, v7, v198
	v_fmac_f32_e32 v195, v72, v200
	v_fmac_f32_e32 v195, v76, v201
	v_add_f32_e32 v194, v194, v195
	s_waitcnt lgkmcnt(1)
	v_mul_f32_e32 v195, v80, v203
	v_fmac_f32_e32 v195, v74, v202
	v_fmac_f32_e32 v195, v77, v204
	v_fmac_f32_e32 v195, v78, v205
	v_add_f32_e32 v194, v194, v195
	s_waitcnt lgkmcnt(0)
	v_mul_f32_e32 v195, v82, v207
	v_fmac_f32_e32 v195, v75, v206
	v_fmac_f32_e32 v195, v79, v208
	v_fmac_f32_e32 v195, v81, v209
	v_add_f32_e32 v194, v194, v195
	v_min_f32_e32 v195, 0, v194
	v_mul_f32_e64 v194, |v194|, s3
	v_exp_f32_e32 v194, v194
	s_nop 0
	v_add_f32_e32 v194, 1.0, v194
	v_cmp_gt_f32_e64 s[22:23], s36, v194
	s_nop 1
	v_cndmask_b32_e64 v196, 0, 32, s[22:23]
	v_ldexp_f32 v194, v194, v196
	v_log_f32_e32 v194, v194
	s_nop 0
	v_mul_f32_e32 v196, 0x3f317217, v194
	v_fma_f32 v196, v194, s37, -v196
	v_fmac_f32_e32 v196, 0x3377d1cf, v194
	v_fmac_f32_e32 v196, 0x3f317217, v194
	v_cmp_lt_f32_e64 s[26:27], |v194|, s38
	s_nop 1
	v_cndmask_b32_e64 v194, v194, v196, s[26:27]
	v_cndmask_b32_e64 v196, 0, v212, s[22:23]
	v_sub_f32_e32 v194, v194, v196
	ds_read_b128 v[196:199], v178
	ds_read_b128 v[200:203], v178 offset:16
	ds_read_b128 v[204:207], v178 offset:32
	ds_read_b128 v[216:219], v178 offset:48
	v_sub_f32_e32 v194, v195, v194
	s_waitcnt lgkmcnt(3)
	v_mul_f32_e32 v195, v5, v197
	v_fmac_f32_e32 v195, v3, v196
	s_waitcnt lgkmcnt(2)
	v_mul_f32_e32 v196, v73, v201
	v_fmac_f32_e32 v195, v4, v198
	v_fmac_f32_e32 v196, v7, v200
	v_fmac_f32_e32 v195, v71, v199
	v_fmac_f32_e32 v196, v72, v202
	v_add_f32_e32 v195, v83, v195
	v_fmac_f32_e32 v196, v76, v203
	v_add_f32_e32 v195, v195, v196
	s_waitcnt lgkmcnt(1)
	v_mul_f32_e32 v196, v80, v205
	v_fmac_f32_e32 v196, v74, v204
	v_fmac_f32_e32 v196, v77, v206
	v_fmac_f32_e32 v196, v78, v207
	v_add_f32_e32 v195, v195, v196
	s_waitcnt lgkmcnt(0)
	v_mul_f32_e32 v196, v82, v217
	v_fmac_f32_e32 v196, v75, v216
	v_fmac_f32_e32 v196, v79, v218
	v_fmac_f32_e32 v196, v81, v219
	v_add_f32_e32 v195, v195, v196
	v_min_f32_e32 v196, 0, v195
	v_mul_f32_e64 v195, |v195|, s3
	v_exp_f32_e32 v195, v195
	v_fmamk_f32 v194, v194, 0x3d800000, v193
	v_add_f32_e32 v195, 1.0, v195
	v_cmp_gt_f32_e64 s[22:23], s36, v195
	s_nop 1
	v_cndmask_b32_e64 v197, 0, 32, s[22:23]
	v_ldexp_f32 v195, v195, v197
	v_log_f32_e32 v195, v195
	s_nop 0
	v_mul_f32_e32 v197, 0x3f317217, v195
	v_fma_f32 v197, v195, s37, -v197
	v_fmac_f32_e32 v197, 0x3377d1cf, v195
	v_fmac_f32_e32 v197, 0x3f317217, v195
	v_cmp_lt_f32_e64 s[26:27], |v195|, s38
	s_nop 1
	v_cndmask_b32_e64 v195, v195, v197, s[26:27]
	v_cndmask_b32_e64 v197, 0, v212, s[22:23]
	v_sub_f32_e32 v195, v195, v197
	v_sub_f32_e32 v195, v196, v195
	ds_read_b128 v[196:199], v179
	ds_read_b128 v[200:203], v179 offset:16
	ds_read_b128 v[204:207], v179 offset:32
	ds_read_b128 v[216:219], v179 offset:48
	v_fmamk_f32 v195, v195, 0x3d800000, v194
	s_waitcnt lgkmcnt(3)
	v_mul_f32_e32 v197, v5, v197
	v_fmac_f32_e32 v197, v3, v196
	v_fmac_f32_e32 v197, v4, v198
	v_fmac_f32_e32 v197, v71, v199
	v_add_f32_e32 v196, v83, v197
	s_waitcnt lgkmcnt(2)
	v_mul_f32_e32 v197, v73, v201
	v_fmac_f32_e32 v197, v7, v200
	v_fmac_f32_e32 v197, v72, v202
	v_fmac_f32_e32 v197, v76, v203
	v_add_f32_e32 v196, v196, v197
	s_waitcnt lgkmcnt(1)
	v_mul_f32_e32 v197, v80, v205
	v_fmac_f32_e32 v197, v74, v204
	v_fmac_f32_e32 v197, v77, v206
	v_fmac_f32_e32 v197, v78, v207
	v_add_f32_e32 v196, v196, v197
	s_waitcnt lgkmcnt(0)
	v_mul_f32_e32 v197, v82, v217
	v_fmac_f32_e32 v197, v75, v216
	v_fmac_f32_e32 v197, v79, v218
	v_fmac_f32_e32 v197, v81, v219
	v_add_f32_e32 v196, v196, v197
	v_min_f32_e32 v197, 0, v196
	v_mul_f32_e64 v196, |v196|, s3
	v_exp_f32_e32 v196, v196
	s_nop 0
	v_add_f32_e32 v196, 1.0, v196
	v_cmp_gt_f32_e64 s[22:23], s36, v196
	s_nop 1
	v_cndmask_b32_e64 v198, 0, 32, s[22:23]
	v_ldexp_f32 v196, v196, v198
	v_log_f32_e32 v196, v196
	s_nop 0
	v_mul_f32_e32 v198, 0x3f317217, v196
	v_fma_f32 v198, v196, s37, -v198
	v_fmac_f32_e32 v198, 0x3377d1cf, v196
	v_fmac_f32_e32 v198, 0x3f317217, v196
	v_cmp_lt_f32_e64 s[26:27], |v196|, s38
	s_nop 1
	v_cndmask_b32_e64 v196, v196, v198, s[26:27]
	v_cndmask_b32_e64 v198, 0, v212, s[22:23]
	v_sub_f32_e32 v196, v196, v198
	ds_read_b128 v[198:201], v180
	ds_read_b128 v[202:205], v180 offset:16
	ds_read_b128 v[206:209], v180 offset:32
	ds_read_b128 v[216:219], v180 offset:48
	v_sub_f32_e32 v196, v197, v196
	s_waitcnt lgkmcnt(3)
	v_mul_f32_e32 v197, v5, v199
	v_fmac_f32_e32 v197, v3, v198
	s_waitcnt lgkmcnt(2)
	v_mul_f32_e32 v198, v73, v203
	v_fmac_f32_e32 v197, v4, v200
	v_fmac_f32_e32 v198, v7, v202
	v_fmac_f32_e32 v197, v71, v201
	v_fmac_f32_e32 v198, v72, v204
	v_add_f32_e32 v197, v83, v197
	v_fmac_f32_e32 v198, v76, v205
	v_add_f32_e32 v197, v197, v198
	s_waitcnt lgkmcnt(1)
	v_mul_f32_e32 v198, v80, v207
	v_fmac_f32_e32 v198, v74, v206
	v_fmac_f32_e32 v198, v77, v208
	v_fmac_f32_e32 v198, v78, v209
	v_add_f32_e32 v197, v197, v198
	s_waitcnt lgkmcnt(0)
	v_mul_f32_e32 v198, v82, v217
	v_fmac_f32_e32 v198, v75, v216
	v_fmac_f32_e32 v198, v79, v218
	v_fmac_f32_e32 v198, v81, v219
	v_add_f32_e32 v197, v197, v198
	v_min_f32_e32 v198, 0, v197
	v_mul_f32_e64 v197, |v197|, s3
	v_exp_f32_e32 v197, v197
	v_fmamk_f32 v196, v196, 0x3d800000, v195
	v_add_f32_e32 v197, 1.0, v197
	v_cmp_gt_f32_e64 s[22:23], s36, v197
	s_nop 1
	v_cndmask_b32_e64 v199, 0, 32, s[22:23]
	v_ldexp_f32 v197, v197, v199
	v_log_f32_e32 v197, v197
	s_nop 0
	v_mul_f32_e32 v199, 0x3f317217, v197
	v_fma_f32 v199, v197, s37, -v199
	v_fmac_f32_e32 v199, 0x3377d1cf, v197
	v_fmac_f32_e32 v199, 0x3f317217, v197
	v_cmp_lt_f32_e64 s[26:27], |v197|, s38
	s_nop 1
	v_cndmask_b32_e64 v197, v197, v199, s[26:27]
	v_cndmask_b32_e64 v199, 0, v212, s[22:23]
	v_sub_f32_e32 v197, v197, v199
	v_sub_f32_e32 v197, v198, v197
	ds_read_b128 v[198:201], v181
	ds_read_b128 v[202:205], v181 offset:16
	ds_read_b128 v[206:209], v181 offset:32
	ds_read_b128 v[216:219], v181 offset:48
	v_fmamk_f32 v197, v197, 0x3d800000, v196
	s_waitcnt lgkmcnt(3)
	v_mul_f32_e32 v199, v5, v199
	v_fmac_f32_e32 v199, v3, v198
	v_fmac_f32_e32 v199, v4, v200
	v_fmac_f32_e32 v199, v71, v201
	v_add_f32_e32 v198, v83, v199
	s_waitcnt lgkmcnt(2)
	v_mul_f32_e32 v199, v73, v203
	v_fmac_f32_e32 v199, v7, v202
	v_fmac_f32_e32 v199, v72, v204
	v_fmac_f32_e32 v199, v76, v205
	v_add_f32_e32 v198, v198, v199
	s_waitcnt lgkmcnt(1)
	v_mul_f32_e32 v199, v80, v207
	v_fmac_f32_e32 v199, v74, v206
	v_fmac_f32_e32 v199, v77, v208
	v_fmac_f32_e32 v199, v78, v209
	v_add_f32_e32 v198, v198, v199
	s_waitcnt lgkmcnt(0)
	v_mul_f32_e32 v199, v82, v217
	v_fmac_f32_e32 v199, v75, v216
	v_fmac_f32_e32 v199, v79, v218
	v_fmac_f32_e32 v199, v81, v219
	v_add_f32_e32 v198, v198, v199
	v_min_f32_e32 v199, 0, v198
	v_mul_f32_e64 v198, |v198|, s3
	v_exp_f32_e32 v198, v198
	s_nop 0
	v_add_f32_e32 v198, 1.0, v198
	v_cmp_gt_f32_e64 s[22:23], s36, v198
	s_nop 1
	v_cndmask_b32_e64 v200, 0, 32, s[22:23]
	v_ldexp_f32 v198, v198, v200
	v_log_f32_e32 v198, v198
	s_nop 0
	v_mul_f32_e32 v200, 0x3f317217, v198
	v_fma_f32 v200, v198, s37, -v200
	v_fmac_f32_e32 v200, 0x3377d1cf, v198
	v_fmac_f32_e32 v200, 0x3f317217, v198
	v_cmp_lt_f32_e64 s[26:27], |v198|, s38
	s_nop 1
	v_cndmask_b32_e64 v198, v198, v200, s[26:27]
	v_cndmask_b32_e64 v200, 0, v212, s[22:23]
	v_sub_f32_e32 v198, v198, v200
	ds_read_b128 v[200:203], v182
	ds_read_b128 v[204:207], v182 offset:16
	ds_read_b128 v[216:219], v182 offset:32
	ds_read_b128 v[220:223], v182 offset:48
	v_sub_f32_e32 v198, v199, v198
	s_waitcnt lgkmcnt(3)
	v_mul_f32_e32 v199, v5, v201
	v_fmac_f32_e32 v199, v3, v200
	s_waitcnt lgkmcnt(2)
	v_mul_f32_e32 v200, v73, v205
	v_fmac_f32_e32 v199, v4, v202
	v_fmac_f32_e32 v200, v7, v204
	v_fmac_f32_e32 v199, v71, v203
	v_fmac_f32_e32 v200, v72, v206
	v_add_f32_e32 v199, v83, v199
	v_fmac_f32_e32 v200, v76, v207
	v_add_f32_e32 v199, v199, v200
	s_waitcnt lgkmcnt(1)
	v_mul_f32_e32 v200, v80, v217
	v_fmac_f32_e32 v200, v74, v216
	v_fmac_f32_e32 v200, v77, v218
	v_fmac_f32_e32 v200, v78, v219
	v_add_f32_e32 v199, v199, v200
	s_waitcnt lgkmcnt(0)
	v_mul_f32_e32 v200, v82, v221
	v_fmac_f32_e32 v200, v75, v220
	v_fmac_f32_e32 v200, v79, v222
	v_fmac_f32_e32 v200, v81, v223
	v_add_f32_e32 v199, v199, v200
	v_min_f32_e32 v200, 0, v199
	v_mul_f32_e64 v199, |v199|, s3
	v_exp_f32_e32 v199, v199
	v_fmamk_f32 v198, v198, 0x3d800000, v197
	v_add_f32_e32 v199, 1.0, v199
	v_cmp_gt_f32_e64 s[22:23], s36, v199
	s_nop 1
	v_cndmask_b32_e64 v201, 0, 32, s[22:23]
	v_ldexp_f32 v199, v199, v201
	v_log_f32_e32 v199, v199
	s_nop 0
	v_mul_f32_e32 v201, 0x3f317217, v199
	v_fma_f32 v201, v199, s37, -v201
	v_fmac_f32_e32 v201, 0x3377d1cf, v199
	v_fmac_f32_e32 v201, 0x3f317217, v199
	v_cmp_lt_f32_e64 s[26:27], |v199|, s38
	s_nop 1
	v_cndmask_b32_e64 v199, v199, v201, s[26:27]
	v_cndmask_b32_e64 v201, 0, v212, s[22:23]
	v_sub_f32_e32 v199, v199, v201
	v_sub_f32_e32 v199, v200, v199
	ds_read_b128 v[200:203], v183
	ds_read_b128 v[204:207], v183 offset:16
	ds_read_b128 v[216:219], v183 offset:32
	ds_read_b128 v[220:223], v183 offset:48
	v_fmamk_f32 v199, v199, 0x3d800000, v198
	s_waitcnt lgkmcnt(3)
	v_mul_f32_e32 v201, v5, v201
	v_fmac_f32_e32 v201, v3, v200
	v_fmac_f32_e32 v201, v4, v202
	v_fmac_f32_e32 v201, v71, v203
	v_add_f32_e32 v200, v83, v201
	s_waitcnt lgkmcnt(2)
	v_mul_f32_e32 v201, v73, v205
	v_fmac_f32_e32 v201, v7, v204
	v_fmac_f32_e32 v201, v72, v206
	v_fmac_f32_e32 v201, v76, v207
	v_add_f32_e32 v200, v200, v201
	s_waitcnt lgkmcnt(1)
	v_mul_f32_e32 v201, v80, v217
	v_fmac_f32_e32 v201, v74, v216
	v_fmac_f32_e32 v201, v77, v218
	v_fmac_f32_e32 v201, v78, v219
	v_add_f32_e32 v200, v200, v201
	s_waitcnt lgkmcnt(0)
	v_mul_f32_e32 v201, v82, v221
	v_fmac_f32_e32 v201, v75, v220
	v_fmac_f32_e32 v201, v79, v222
	v_fmac_f32_e32 v201, v81, v223
	v_add_f32_e32 v200, v200, v201
	v_min_f32_e32 v201, 0, v200
	v_mul_f32_e64 v200, |v200|, s3
	v_exp_f32_e32 v200, v200
	s_nop 0
	v_add_f32_e32 v200, 1.0, v200
	v_cmp_gt_f32_e64 s[22:23], s36, v200
	s_nop 1
	v_cndmask_b32_e64 v202, 0, 32, s[22:23]
	v_ldexp_f32 v200, v200, v202
	v_log_f32_e32 v200, v200
	s_nop 0
	v_mul_f32_e32 v202, 0x3f317217, v200
	v_fma_f32 v202, v200, s37, -v202
	v_fmac_f32_e32 v202, 0x3377d1cf, v200
	v_fmac_f32_e32 v202, 0x3f317217, v200
	v_cmp_lt_f32_e64 s[26:27], |v200|, s38
	s_nop 1
	v_cndmask_b32_e64 v200, v200, v202, s[26:27]
	v_cndmask_b32_e64 v202, 0, v212, s[22:23]
	v_sub_f32_e32 v200, v200, v202
	ds_read_b128 v[202:205], v184
	ds_read_b128 v[206:209], v184 offset:16
	ds_read_b128 v[216:219], v184 offset:32
	ds_read_b128 v[220:223], v184 offset:48
	v_sub_f32_e32 v200, v201, v200
	s_waitcnt lgkmcnt(3)
	v_mul_f32_e32 v201, v5, v203
	v_fmac_f32_e32 v201, v3, v202
	s_waitcnt lgkmcnt(2)
	v_mul_f32_e32 v202, v73, v207
	v_fmac_f32_e32 v201, v4, v204
	v_fmac_f32_e32 v202, v7, v206
	v_fmac_f32_e32 v201, v71, v205
	v_fmac_f32_e32 v202, v72, v208
	v_add_f32_e32 v201, v83, v201
	v_fmac_f32_e32 v202, v76, v209
	v_add_f32_e32 v201, v201, v202
	s_waitcnt lgkmcnt(1)
	v_mul_f32_e32 v202, v80, v217
	v_fmac_f32_e32 v202, v74, v216
	v_fmac_f32_e32 v202, v77, v218
	v_fmac_f32_e32 v202, v78, v219
	v_add_f32_e32 v201, v201, v202
	s_waitcnt lgkmcnt(0)
	v_mul_f32_e32 v202, v82, v221
	v_fmac_f32_e32 v202, v75, v220
	v_fmac_f32_e32 v202, v79, v222
	v_fmac_f32_e32 v202, v81, v223
	v_add_f32_e32 v201, v201, v202
	v_min_f32_e32 v202, 0, v201
	v_mul_f32_e64 v201, |v201|, s3
	v_exp_f32_e32 v201, v201
	v_fmamk_f32 v200, v200, 0x3d800000, v199
	v_add_f32_e32 v201, 1.0, v201
	v_cmp_gt_f32_e64 s[22:23], s36, v201
	s_nop 1
	v_cndmask_b32_e64 v203, 0, 32, s[22:23]
	v_ldexp_f32 v201, v201, v203
	v_log_f32_e32 v201, v201
	s_nop 0
	v_mul_f32_e32 v203, 0x3f317217, v201
	v_fma_f32 v203, v201, s37, -v203
	v_fmac_f32_e32 v203, 0x3377d1cf, v201
	v_fmac_f32_e32 v203, 0x3f317217, v201
	v_cmp_lt_f32_e64 s[26:27], |v201|, s38
	s_nop 1
	v_cndmask_b32_e64 v201, v201, v203, s[26:27]
	v_cndmask_b32_e64 v203, 0, v212, s[22:23]
	v_sub_f32_e32 v201, v201, v203
	v_sub_f32_e32 v201, v202, v201
	ds_read_b128 v[202:205], v185
	ds_read_b128 v[206:209], v185 offset:16
	ds_read_b128 v[216:219], v185 offset:32
	ds_read_b128 v[220:223], v185 offset:48
	v_fmamk_f32 v201, v201, 0x3d800000, v200
	s_waitcnt lgkmcnt(3)
	v_mul_f32_e32 v5, v5, v203
	v_fmac_f32_e32 v5, v3, v202
	v_fmac_f32_e32 v5, v4, v204
	s_waitcnt lgkmcnt(2)
	v_mul_f32_e32 v4, v73, v207
	v_fmac_f32_e32 v4, v7, v206
	v_fmac_f32_e32 v5, v71, v205
	v_fmac_f32_e32 v4, v72, v208
	v_add_f32_e32 v3, v83, v5
	v_fmac_f32_e32 v4, v76, v209
	v_add_f32_e32 v3, v3, v4
	s_waitcnt lgkmcnt(1)
	v_mul_f32_e32 v4, v80, v217
	v_fmac_f32_e32 v4, v74, v216
	v_fmac_f32_e32 v4, v77, v218
	v_fmac_f32_e32 v4, v78, v219
	v_add_f32_e32 v3, v3, v4
	s_waitcnt lgkmcnt(0)
	v_mul_f32_e32 v4, v82, v221
	v_fmac_f32_e32 v4, v75, v220
	v_fmac_f32_e32 v4, v79, v222
	v_fmac_f32_e32 v4, v81, v223
	v_add_f32_e32 v3, v3, v4
	v_min_f32_e32 v4, 0, v3
	v_mul_f32_e64 v3, |v3|, s3
	v_exp_f32_e32 v3, v3
	s_nop 0
	v_add_f32_e32 v3, 1.0, v3
	v_cmp_gt_f32_e64 s[22:23], s36, v3
	s_nop 1
	v_cndmask_b32_e64 v5, 0, 32, s[22:23]
	v_ldexp_f32 v3, v3, v5
	v_log_f32_e32 v3, v3
	s_nop 0
	v_mul_f32_e32 v5, 0x3f317217, v3
	v_fma_f32 v5, v3, s37, -v5
	v_fmac_f32_e32 v5, 0x3377d1cf, v3
	v_fmac_f32_e32 v5, 0x3f317217, v3
	v_cmp_lt_f32_e64 s[26:27], |v3|, s38
	s_nop 1
	v_cndmask_b32_e64 v3, v3, v5, s[26:27]
	v_cndmask_b32_e64 v5, 0, v212, s[22:23]
	v_sub_f32_e32 v3, v3, v5
	v_sub_f32_e32 v3, v4, v3
	v_fmamk_f32 v7, v3, 0x3d800000, v201
	ds_write_b32 v118, v7
	s_waitcnt lgkmcnt(0)
	s_barrier
	ds_read2st64_b32 v[4:5], v119 offset1:4
	s_waitcnt lgkmcnt(0)
	v_add_f32_e32 v5, v4, v5
	s_and_saveexec_b64 s[2:3], vcc
	s_cbranch_execz .LBB0_442
	v_mul_f32_e32 v3, 0x3fb8aa3b, v5
	v_exp_f32_e32 v3, v3
	s_lshl_b64 s[22:23], s[96:97], 10
	v_lshl_add_u64 v[72:73], v[96:97], 0, s[22:23]
	global_store_dword v[72:73], v3, off
